# ssd1 prompt conv+SiLU loop: 8 token chains interleaved, LDS reads batched and prefetched one trip ahead
# speedup vs baseline: 1.0048x; 1.0026x over previous
.LBB0_1076:
	s_or_b64 exec, exec, s[16:17]
	s_waitcnt lgkmcnt(0)
	s_barrier
	s_and_saveexec_b64 s[0:1], s[38:39]
	s_cbranch_execz .LBB0_1022
	s_movk_i32 s16, 0xff
	v_cmp_lt_i32_e32 vcc, s16, v158
	s_add_i32 s16, 0, 0xe400
	s_lshl_b64 s[2:3], s[14:15], 15
	v_mul_lo_u32 v2, v158, s36
	v_lshl_add_u32 v9, v158, 1, s16
	s_add_i32 s16, 0, 0xe000
	v_add_u32_e32 v8, 0, v2
	v_lshlrev_b32_e32 v2, 6, v158
	s_add_u32 s2, s27, s2
	v_ashrrev_i32_e32 v3, 31, v2
	s_addc_u32 s3, s28, s3
	v_lshl_add_u32 v10, v160, 2, s16
	v_lshl_add_u64 v[6:7], v[2:3], 1, s[2:3]
	s_mov_b32 s16, 0
	ds_read_u16 v38, v9
	ds_read_u16 v39, v9 offset:768
	ds_read_u16 v40, v9 offset:1536
	ds_read_u16 v41, v9 offset:2304
	ds_read_u16 v42, v9 offset:3072
	ds_read_u16 v43, v9 offset:3840
	ds_read_u16 v44, v9 offset:4608
	ds_read_u16 v45, v9 offset:5376
	ds_read_u16 v46, v9 offset:6144
	ds_read_u16 v47, v9 offset:6912
	ds_read_u16 v48, v9 offset:7680
	s_branch .LBB0_1079

.LBB0_1079:
	s_waitcnt lgkmcnt(0)
	v_lshlrev_b32_e32 v19, 16, v38
	v_lshlrev_b32_e32 v20, 16, v39
	v_lshlrev_b32_e32 v21, 16, v40
	v_lshlrev_b32_e32 v22, 16, v41
	v_lshlrev_b32_e32 v23, 16, v42
	v_lshlrev_b32_e32 v24, 16, v43
	v_lshlrev_b32_e32 v25, 16, v44
	v_lshlrev_b32_e32 v26, 16, v45
	v_lshlrev_b32_e32 v27, 16, v46
	v_lshlrev_b32_e32 v28, 16, v47
	v_lshlrev_b32_e32 v29, 16, v48
	ds_read_u16 v38, v9 offset:6144
	ds_read_u16 v39, v9 offset:6912
	ds_read_u16 v40, v9 offset:7680
	ds_read_u16 v41, v9 offset:8448
	ds_read_u16 v42, v9 offset:9216
	ds_read_u16 v43, v9 offset:9984
	ds_read_u16 v44, v9 offset:10752
	ds_read_u16 v45, v9 offset:11520
	ds_read_u16 v46, v9 offset:12288
	ds_read_u16 v47, v9 offset:13056
	ds_read_u16 v48, v9 offset:13824
	v_fma_f32 v11, v159, v19, v226
	v_fma_f32 v12, v159, v20, v226
	v_fma_f32 v13, v159, v21, v226
	v_fma_f32 v14, v159, v22, v226
	v_fma_f32 v15, v159, v23, v226
	v_fma_f32 v16, v159, v24, v226
	v_fma_f32 v17, v159, v25, v226
	v_fma_f32 v18, v159, v26, v226
	v_fmac_f32_e32 v11, v181, v20
	v_fmac_f32_e32 v12, v181, v21
	v_fmac_f32_e32 v13, v181, v22
	v_fmac_f32_e32 v14, v181, v23
	v_fmac_f32_e32 v15, v181, v24
	v_fmac_f32_e32 v16, v181, v25
	v_fmac_f32_e32 v17, v181, v26
	v_fmac_f32_e32 v18, v181, v27
	v_fmac_f32_e32 v11, v199, v21
	v_fmac_f32_e32 v12, v199, v22
	v_fmac_f32_e32 v13, v199, v23
	v_fmac_f32_e32 v14, v199, v24
	v_fmac_f32_e32 v15, v199, v25
	v_fmac_f32_e32 v16, v199, v26
	v_fmac_f32_e32 v17, v199, v27
	v_fmac_f32_e32 v18, v199, v28
	v_fmac_f32_e32 v11, v203, v22
	v_fmac_f32_e32 v12, v203, v23
	v_fmac_f32_e32 v13, v203, v24
	v_fmac_f32_e32 v14, v203, v25
	v_fmac_f32_e32 v15, v203, v26
	v_fmac_f32_e32 v16, v203, v27
	v_fmac_f32_e32 v17, v203, v28
	v_fmac_f32_e32 v18, v203, v29
	v_mul_f32_e32 v30, 0xbfb8aa3b, v11
	v_mul_f32_e32 v31, 0xbfb8aa3b, v12
	v_mul_f32_e32 v32, 0xbfb8aa3b, v13
	v_mul_f32_e32 v33, 0xbfb8aa3b, v14
	v_mul_f32_e32 v34, 0xbfb8aa3b, v15
	v_mul_f32_e32 v35, 0xbfb8aa3b, v16
	v_mul_f32_e32 v36, 0xbfb8aa3b, v17
	v_mul_f32_e32 v37, 0xbfb8aa3b, v18
	v_exp_f32_e32 v30, v30
	v_exp_f32_e32 v31, v31
	v_exp_f32_e32 v32, v32
	v_exp_f32_e32 v33, v33
	v_exp_f32_e32 v34, v34
	v_exp_f32_e32 v35, v35
	v_exp_f32_e32 v36, v36
	v_exp_f32_e32 v37, v37
	v_add_f32_e32 v30, 1.0, v30
	v_add_f32_e32 v31, 1.0, v31
	v_add_f32_e32 v32, 1.0, v32
	v_add_f32_e32 v33, 1.0, v33
	v_add_f32_e32 v34, 1.0, v34
	v_add_f32_e32 v35, 1.0, v35
	v_add_f32_e32 v36, 1.0, v36
	v_add_f32_e32 v37, 1.0, v37
	v_rcp_f32_e32 v30, v30
	v_rcp_f32_e32 v31, v31
	v_rcp_f32_e32 v32, v32
	v_rcp_f32_e32 v33, v33
	v_rcp_f32_e32 v34, v34
	v_rcp_f32_e32 v35, v35
	v_rcp_f32_e32 v36, v36
	v_rcp_f32_e32 v37, v37
	v_mul_f32_e32 v11, v11, v30
	v_mul_f32_e32 v12, v12, v31
	v_mul_f32_e32 v13, v13, v32
	v_mul_f32_e32 v14, v14, v33
	v_mul_f32_e32 v15, v15, v34
	v_mul_f32_e32 v16, v16, v35
	v_mul_f32_e32 v17, v17, v36
	v_mul_f32_e32 v18, v18, v37
	s_and_saveexec_b64 s[2:3], vcc
	s_xor_b64 s[2:3], exec, s[2:3]
	s_cbranch_execz .LBB0_1081
	v_cvt_pk_bf16_f32 v2, v11, v12
	v_cvt_pk_bf16_f32 v3, v13, v14
	v_cvt_pk_bf16_f32 v4, v15, v16
	v_cvt_pk_bf16_f32 v5, v17, v18
